# v13 + gate epilogue: L2 touch-prefetch of the second half's Y lines during the first half's sigmoid work
# baseline (speedup 1.0000x reference)
.LBB0_187:
	s_and_b64 vcc, exec, s[0:1]
	s_cbranch_vccz .LBB0_189
	v_lshl_or_b32 v130, s95, 6, v235
	s_waitcnt lgkmcnt(0)
	v_ashrrev_i32_e32 v131, 31, v130
	v_lshlrev_b64 v[130:131], 1, v[130:131]
	v_ashrrev_i32_e32 v185, 31, v184
	v_lshl_add_u64 v[132:133], s[2:3], 0, v[130:131]
	v_lshlrev_b64 v[134:135], 14, v[184:185]
	v_lshl_add_u64 v[134:135], v[132:133], 0, v[134:135]
	v_add_co_u32_e32 v136, vcc, 0x1000, v134
	v_or_b32_e32 v154, 16, v184
	s_nop 0
	v_addc_co_u32_e32 v137, vcc, 0, v135, vcc
	v_add_co_u32_e32 v138, vcc, s99, v134
	v_ashrrev_i32_e32 v155, 31, v154
	s_nop 0
	v_addc_co_u32_e32 v139, vcc, 0, v135, vcc
	v_add_co_u32_e32 v140, vcc, 0x3000, v134
	v_or_b32_e32 v144, 32, v184
	s_nop 0
	v_addc_co_u32_e32 v141, vcc, 0, v135, vcc
	global_load_dwordx2 v[164:165], v[134:135], off
	global_load_dwordx2 v[166:167], v[136:137], off
	global_load_dwordx2 v[168:169], v[138:139], off
	global_load_dwordx2 v[188:189], v[140:141], off
	v_lshlrev_b64 v[134:135], 14, v[154:155]
	v_lshl_add_u64 v[134:135], v[132:133], 0, v[134:135]
	v_add_co_u32_e32 v140, vcc, s99, v134
	v_ashrrev_i32_e32 v145, 31, v144
	s_nop 0
	v_addc_co_u32_e32 v141, vcc, 0, v135, vcc
	v_add_co_u32_e32 v136, vcc, s56, v134
	v_lshlrev_b64 v[138:139], 14, v[144:145]
	s_nop 0
	v_addc_co_u32_e32 v137, vcc, 0, v135, vcc
	v_lshl_add_u64 v[138:139], v[132:133], 0, v[138:139]
	v_add_co_u32_e32 v142, vcc, s99, v138
	v_lshlrev_b64 v[154:155], 12, v[154:155]
	s_nop 0
	v_addc_co_u32_e32 v143, vcc, 0, v139, vcc
	v_add_co_u32_e32 v146, vcc, s56, v138
	v_lshl_add_u64 v[154:155], s[30:31], 0, v[154:155]
	s_nop 0
	v_addc_co_u32_e32 v147, vcc, 0, v139, vcc
	global_load_dwordx2 v[158:159], v[134:135], off
	global_load_dwordx2 v[156:157], v[136:137], off
	global_load_dwordx2 v[148:149], v[138:139], off
	s_nop 0
	global_load_dwordx2 v[146:147], v[146:147], off
	v_or_b32_e32 v134, 48, v184
	v_ashrrev_i32_e32 v135, 31, v134
	v_lshlrev_b64 v[136:137], 14, v[134:135]
	v_lshl_add_u64 v[190:191], v[132:133], 0, v[136:137]
	v_add_co_u32_e32 v136, vcc, s99, v190
	v_lshl_add_u64 v[154:155], v[154:155], 0, v[130:131]
	s_nop 0
	v_addc_co_u32_e32 v137, vcc, 0, v191, vcc
	global_load_dwordx2 v[152:153], v[142:143], off offset:-4096
	global_load_dwordx2 v[150:151], v[142:143], off
	global_load_dwordx2 v[138:139], v[136:137], off offset:-4096
	s_nop 0
	global_load_dwordx2 v[136:137], v[136:137], off
	v_mul_f32_e32 v142, 0xbfb8aa3b, v122
	v_add_co_u32_e32 v192, vcc, s56, v190
	v_exp_f32_e32 v187, v142
	v_mul_f32_e32 v142, 0xbfb8aa3b, v123
	v_addc_co_u32_e32 v193, vcc, 0, v191, vcc
	v_exp_f32_e32 v194, v142
	global_load_dwordx2 v[162:163], v[140:141], off offset:-4096
	global_load_dwordx2 v[160:161], v[140:141], off
	global_load_dwordx2 v[142:143], v[190:191], off
	s_nop 0
	global_load_dwordx2 v[140:141], v[192:193], off
	v_mul_f32_e32 v191, 0xbfb8aa3b, v124
	v_exp_f32_e32 v192, v191
	v_mul_f32_e32 v191, 0xbfb8aa3b, v125
	v_exp_f32_e32 v193, v191
	v_add_f32_e32 v187, 1.0, v187
	v_rcp_f32_e32 v190, v187
	v_add_f32_e32 v187, 1.0, v194
	v_rcp_f32_e32 v191, v187
	v_add_f32_e32 v187, 1.0, v192
	v_rcp_f32_e32 v192, v187
	v_add_f32_e32 v187, 1.0, v193
	v_mul_f32_e32 v193, 0xbfb8aa3b, v126
	v_exp_f32_e32 v194, v193
	v_mul_f32_e32 v193, 0xbfb8aa3b, v127
	v_exp_f32_e32 v195, v193
	v_rcp_f32_e32 v193, v187
	v_add_f32_e32 v187, 1.0, v194
	v_rcp_f32_e32 v194, v187
	v_add_f32_e32 v187, 1.0, v195
	v_mul_f32_e32 v195, 0xbfb8aa3b, v128
	v_exp_f32_e32 v196, v195
	v_mul_f32_e32 v195, 0xbfb8aa3b, v129
	v_exp_f32_e32 v197, v195
	v_rcp_f32_e32 v195, v187
	v_add_f32_e32 v187, 1.0, v196
	v_rcp_f32_e32 v196, v187
	v_add_f32_e32 v187, 1.0, v197
	v_mul_f32_e32 v197, 0xbfb8aa3b, v114
	v_exp_f32_e32 v198, v197
	v_mul_f32_e32 v197, 0xbfb8aa3b, v115
	v_exp_f32_e32 v199, v197
	v_rcp_f32_e32 v197, v187
	v_add_f32_e32 v187, 1.0, v198
	v_rcp_f32_e32 v198, v187
	v_add_f32_e32 v187, 1.0, v199
	v_mul_f32_e32 v199, 0xbfb8aa3b, v116
	v_exp_f32_e32 v200, v199
	v_mul_f32_e32 v199, 0xbfb8aa3b, v117
	v_exp_f32_e32 v201, v199
	v_rcp_f32_e32 v199, v187
	v_add_f32_e32 v187, 1.0, v200
	v_rcp_f32_e32 v200, v187
	v_add_f32_e32 v187, 1.0, v201
	v_mul_f32_e32 v201, 0xbfb8aa3b, v118
	v_exp_f32_e32 v202, v201
	v_mul_f32_e32 v201, 0xbfb8aa3b, v119
	v_exp_f32_e32 v203, v201
	v_rcp_f32_e32 v201, v187
	v_add_f32_e32 v187, 1.0, v202
	s_waitcnt vmcnt(0)
	v_mov_b32_e32 v249, 0
	v_lshlrev_b32_e32 v248, 2, v184
	v_add_u32_e32 v248, 0x201, v248
	v_lshl_add_u64 v[246:247], v[248:249], 12, v[132:133]
	global_load_dword v214, v[246:247], off offset:-4096
	global_load_dword v215, v[246:247], off
	v_add_u32_e32 v248, 2, v248
	v_lshl_add_u64 v[246:247], v[248:249], 12, v[132:133]
	global_load_dword v216, v[246:247], off offset:-4096
	global_load_dword v217, v[246:247], off
	v_add_u32_e32 v248, 62, v248
	v_lshl_add_u64 v[246:247], v[248:249], 12, v[132:133]
	global_load_dword v218, v[246:247], off offset:-4096
	global_load_dword v219, v[246:247], off
	v_add_u32_e32 v248, 2, v248
	v_lshl_add_u64 v[246:247], v[248:249], 12, v[132:133]
	global_load_dword v220, v[246:247], off offset:-4096
	global_load_dword v221, v[246:247], off
	v_add_u32_e32 v248, 62, v248
	v_lshl_add_u64 v[246:247], v[248:249], 12, v[132:133]
	global_load_dword v239, v[246:247], off offset:-4096
	global_load_dword v240, v[246:247], off
	v_add_u32_e32 v248, 2, v248
	v_lshl_add_u64 v[246:247], v[248:249], 12, v[132:133]
	global_load_dword v241, v[246:247], off offset:-4096
	global_load_dword v242, v[246:247], off
	v_add_u32_e32 v248, 62, v248
	v_lshl_add_u64 v[246:247], v[248:249], 12, v[132:133]
	global_load_dword v244, v[246:247], off offset:-4096
	global_load_dword v245, v[246:247], off
	v_add_u32_e32 v248, 2, v248
	v_lshl_add_u64 v[246:247], v[248:249], 12, v[132:133]
	global_load_dword v214, v[246:247], off offset:-4096
	global_load_dword v215, v[246:247], off
	v_lshlrev_b32_e32 v204, 16, v164
	v_and_b32_e32 v205, 0xffff0000, v164
	v_mul_f32_e32 v164, 0xbfb8aa3b, v120
	v_rcp_f32_e32 v202, v187
	v_add_f32_e32 v187, 1.0, v203
	v_pk_fma_f32 v[190:191], v[190:191], v[204:205], 0 op_sel_hi:[1,1,0]
	v_lshlrev_b32_e32 v204, 16, v166
	v_and_b32_e32 v205, 0xffff0000, v166
	v_exp_f32_e32 v164, v164
	v_mul_f32_e32 v166, 0xbfb8aa3b, v121
	v_rcp_f32_e32 v203, v187
	v_exp_f32_e32 v166, v166
	v_pk_fma_f32 v[190:191], v[194:195], v[204:205], v[190:191]
	v_lshlrev_b32_e32 v194, 16, v168
	v_and_b32_e32 v195, 0xffff0000, v168
	v_pk_fma_f32 v[190:191], v[198:199], v[194:195], v[190:191]
	v_lshlrev_b32_e32 v194, 16, v188
	v_and_b32_e32 v195, 0xffff0000, v188
	v_add_f32_e32 v164, 1.0, v164
	v_pk_fma_f32 v[190:191], v[202:203], v[194:195], v[190:191]
	v_rcp_f32_e32 v194, v164
	v_add_f32_e32 v164, 1.0, v166
	v_rcp_f32_e32 v195, v164
	v_lshlrev_b32_e32 v164, 16, v165
	v_and_b32_e32 v165, 0xffff0000, v165
	v_pk_fma_f32 v[164:165], v[192:193], v[164:165], 0 op_sel_hi:[1,1,0]
	v_lshlrev_b32_e32 v166, 16, v167
	v_and_b32_e32 v167, 0xffff0000, v167
	v_pk_fma_f32 v[164:165], v[196:197], v[166:167], v[164:165]
	v_lshlrev_b32_e32 v166, 16, v169
	v_and_b32_e32 v167, 0xffff0000, v169
	v_pk_fma_f32 v[164:165], v[200:201], v[166:167], v[164:165]
	v_lshlrev_b32_e32 v166, 16, v189
	v_and_b32_e32 v167, 0xffff0000, v189
	v_pk_fma_f32 v[164:165], v[194:195], v[166:167], v[164:165]
	v_mul_f32_e32 v187, 0xbfb8aa3b, v113
	v_cvt_pk_bf16_f32 v167, v164, v165
	v_lshlrev_b64 v[164:165], 12, v[184:185]
	v_mul_f32_e32 v185, 0xbfb8aa3b, v112
	v_exp_f32_e32 v185, v185
	v_exp_f32_e32 v187, v187
	v_mul_f32_e32 v168, 0xbfb8aa3b, v106
	v_mul_f32_e32 v169, 0xbfb8aa3b, v107
	v_add_f32_e32 v185, 1.0, v185
	v_exp_f32_e32 v168, v168
	v_exp_f32_e32 v169, v169
	v_rcp_f32_e32 v188, v185
	v_add_f32_e32 v185, 1.0, v187
	v_mul_f32_e32 v187, 0xbfb8aa3b, v98
	v_exp_f32_e32 v187, v187
	v_mul_f32_e32 v189, 0xbfb8aa3b, v99
	v_cvt_pk_bf16_f32 v166, v190, v191
	v_lshl_add_u64 v[164:165], s[30:31], 0, v[164:165]
	v_exp_f32_e32 v191, v189
	v_lshl_add_u64 v[164:165], v[164:165], 0, v[130:131]
	global_store_dwordx2 v[164:165], v[166:167], off
	v_add_f32_e32 v164, 1.0, v168
	v_add_f32_e32 v165, 1.0, v169
	v_mul_f32_e32 v168, 0xbfb8aa3b, v110
	v_mul_f32_e32 v169, 0xbfb8aa3b, v111
	v_exp_f32_e32 v168, v168
	v_exp_f32_e32 v169, v169
	v_rcp_f32_e32 v189, v185
	v_add_f32_e32 v185, 1.0, v187
	v_mul_f32_e32 v187, 0xbfb8aa3b, v100
	v_rcp_f32_e32 v190, v185
	v_add_f32_e32 v185, 1.0, v191
	v_exp_f32_e32 v187, v187
	v_mul_f32_e32 v191, 0xbfb8aa3b, v101
	v_exp_f32_e32 v193, v191
	v_rcp_f32_e32 v164, v164
	v_rcp_f32_e32 v165, v165
	v_add_f32_e32 v168, 1.0, v168
	v_add_f32_e32 v169, 1.0, v169
	v_rcp_f32_e32 v168, v168
	v_rcp_f32_e32 v169, v169
	v_rcp_f32_e32 v191, v185
	v_add_f32_e32 v185, 1.0, v187
	v_mul_f32_e32 v187, 0xbfb8aa3b, v102
	v_rcp_f32_e32 v192, v185
	v_add_f32_e32 v185, 1.0, v193
	v_exp_f32_e32 v187, v187
	v_mul_f32_e32 v193, 0xbfb8aa3b, v103
	v_exp_f32_e32 v195, v193
	v_lshlrev_b32_e32 v196, 16, v158
	v_and_b32_e32 v197, 0xffff0000, v158
	v_mul_f32_e32 v166, 0xbfb8aa3b, v108
	v_mul_f32_e32 v167, 0xbfb8aa3b, v109
	v_pk_fma_f32 v[164:165], v[164:165], v[196:197], 0 op_sel_hi:[1,1,0]
	v_lshlrev_b32_e32 v196, 16, v162
	v_and_b32_e32 v197, 0xffff0000, v162
	v_exp_f32_e32 v166, v166
	v_exp_f32_e32 v167, v167
	v_pk_fma_f32 v[164:165], v[168:169], v[196:197], v[164:165]
	v_lshlrev_b32_e32 v168, 16, v160
	v_and_b32_e32 v169, 0xffff0000, v160
	v_rcp_f32_e32 v193, v185
	v_add_f32_e32 v185, 1.0, v187
	v_pk_fma_f32 v[164:165], v[190:191], v[168:169], v[164:165]
	v_lshlrev_b32_e32 v168, 16, v156
	v_and_b32_e32 v169, 0xffff0000, v156
	v_mul_f32_e32 v156, 0xbfb8aa3b, v104
	v_rcp_f32_e32 v194, v185
	v_add_f32_e32 v185, 1.0, v195
	v_exp_f32_e32 v156, v156
	v_mul_f32_e32 v158, 0xbfb8aa3b, v105
	v_rcp_f32_e32 v195, v185
	v_exp_f32_e32 v158, v158
	v_add_f32_e32 v166, 1.0, v166
	v_add_f32_e32 v167, 1.0, v167
	v_rcp_f32_e32 v166, v166
	v_rcp_f32_e32 v167, v167
	v_add_f32_e32 v156, 1.0, v156
	v_pk_fma_f32 v[164:165], v[194:195], v[168:169], v[164:165]
	v_rcp_f32_e32 v168, v156
	v_add_f32_e32 v156, 1.0, v158
	v_rcp_f32_e32 v169, v156
	v_lshlrev_b32_e32 v158, 16, v159
	v_and_b32_e32 v159, 0xffff0000, v159
	v_pk_fma_f32 v[158:159], v[166:167], v[158:159], 0 op_sel_hi:[1,1,0]
	v_lshlrev_b32_e32 v162, 16, v163
	v_and_b32_e32 v163, 0xffff0000, v163
	v_pk_fma_f32 v[158:159], v[188:189], v[162:163], v[158:159]
	v_lshlrev_b32_e32 v160, 16, v161
	v_and_b32_e32 v161, 0xffff0000, v161
	v_pk_fma_f32 v[158:159], v[192:193], v[160:161], v[158:159]
	v_lshlrev_b32_e32 v156, 16, v157
	v_and_b32_e32 v157, 0xffff0000, v157
	v_pk_fma_f32 v[156:157], v[168:169], v[156:157], v[158:159]
	v_cvt_pk_bf16_f32 v158, v164, v165
	v_cvt_pk_bf16_f32 v159, v156, v157
	v_mul_f32_e32 v156, 0xbfb8aa3b, v90
	v_mul_f32_e32 v157, 0xbfb8aa3b, v91
	v_exp_f32_e32 v156, v156
	v_exp_f32_e32 v157, v157
	global_store_dwordx2 v[154:155], v[158:159], off
	v_mul_f32_e32 v158, 0xbfb8aa3b, v94
	v_mul_f32_e32 v159, 0xbfb8aa3b, v95
	v_exp_f32_e32 v158, v158
	v_exp_f32_e32 v159, v159
	v_mul_f32_e32 v162, 0xbfb8aa3b, v82
	v_mul_f32_e32 v163, 0xbfb8aa3b, v83
	v_exp_f32_e32 v162, v162
	v_exp_f32_e32 v163, v163
	v_add_f32_e32 v154, 1.0, v156
	v_add_f32_e32 v155, 1.0, v157
	v_rcp_f32_e32 v154, v154
	v_rcp_f32_e32 v155, v155
	v_add_f32_e32 v158, 1.0, v158
	v_add_f32_e32 v159, 1.0, v159
	v_rcp_f32_e32 v158, v158
	v_rcp_f32_e32 v159, v159
	v_add_f32_e32 v162, 1.0, v162
	v_add_f32_e32 v163, 1.0, v163
	v_rcp_f32_e32 v162, v162
	v_rcp_f32_e32 v163, v163
	v_mul_f32_e32 v166, 0xbfb8aa3b, v86
	v_mul_f32_e32 v167, 0xbfb8aa3b, v87
	v_exp_f32_e32 v166, v166
	v_exp_f32_e32 v167, v167
	v_lshlrev_b32_e32 v168, 16, v148
	v_and_b32_e32 v169, 0xffff0000, v148
	v_mul_f32_e32 v156, 0xbfb8aa3b, v92
	v_mul_f32_e32 v157, 0xbfb8aa3b, v93
	v_pk_fma_f32 v[154:155], v[154:155], v[168:169], 0 op_sel_hi:[1,1,0]
	v_lshlrev_b32_e32 v168, 16, v152
	v_and_b32_e32 v169, 0xffff0000, v152
	v_exp_f32_e32 v156, v156
	v_exp_f32_e32 v157, v157
	v_mul_f32_e32 v160, 0xbfb8aa3b, v96
	v_mul_f32_e32 v161, 0xbfb8aa3b, v97
	v_pk_fma_f32 v[154:155], v[158:159], v[168:169], v[154:155]
	v_lshlrev_b32_e32 v158, 16, v150
	v_and_b32_e32 v159, 0xffff0000, v150
	v_exp_f32_e32 v160, v160
	v_exp_f32_e32 v161, v161
	v_mul_f32_e32 v164, 0xbfb8aa3b, v84
	v_mul_f32_e32 v165, 0xbfb8aa3b, v85
	v_pk_fma_f32 v[154:155], v[162:163], v[158:159], v[154:155]
	v_lshlrev_b32_e32 v158, 16, v146
	v_and_b32_e32 v159, 0xffff0000, v146
	v_mul_f32_e32 v146, 0xbfb8aa3b, v88
	v_exp_f32_e32 v164, v164
	v_exp_f32_e32 v165, v165
	v_add_f32_e32 v166, 1.0, v166
	v_add_f32_e32 v167, 1.0, v167
	v_exp_f32_e32 v146, v146
	v_mul_f32_e32 v148, 0xbfb8aa3b, v89
	v_rcp_f32_e32 v166, v166
	v_rcp_f32_e32 v167, v167
	v_exp_f32_e32 v148, v148
	v_add_f32_e32 v156, 1.0, v156
	v_add_f32_e32 v157, 1.0, v157
	v_rcp_f32_e32 v156, v156
	v_rcp_f32_e32 v157, v157
	v_add_f32_e32 v160, 1.0, v160
	v_add_f32_e32 v161, 1.0, v161
	v_rcp_f32_e32 v160, v160
	v_rcp_f32_e32 v161, v161
	v_add_f32_e32 v164, 1.0, v164
	v_add_f32_e32 v165, 1.0, v165
	v_add_f32_e32 v146, 1.0, v146
	v_rcp_f32_e32 v164, v164
	v_rcp_f32_e32 v165, v165
	v_pk_fma_f32 v[154:155], v[166:167], v[158:159], v[154:155]
	v_rcp_f32_e32 v158, v146
	v_add_f32_e32 v146, 1.0, v148
	v_rcp_f32_e32 v159, v146
	v_lshlrev_b32_e32 v148, 16, v149
	v_and_b32_e32 v149, 0xffff0000, v149
	v_pk_fma_f32 v[148:149], v[156:157], v[148:149], 0 op_sel_hi:[1,1,0]
	v_lshlrev_b32_e32 v152, 16, v153
	v_and_b32_e32 v153, 0xffff0000, v153
	v_pk_fma_f32 v[148:149], v[160:161], v[152:153], v[148:149]
	v_lshlrev_b32_e32 v150, 16, v151
	v_and_b32_e32 v151, 0xffff0000, v151
	v_pk_fma_f32 v[148:149], v[164:165], v[150:151], v[148:149]
	v_lshlrev_b32_e32 v146, 16, v147
	v_and_b32_e32 v147, 0xffff0000, v147
	v_lshlrev_b64 v[144:145], 12, v[144:145]
	v_pk_fma_f32 v[146:147], v[158:159], v[146:147], v[148:149]
	v_lshl_add_u64 v[144:145], s[30:31], 0, v[144:145]
	v_cvt_pk_bf16_f32 v148, v154, v155
	v_cvt_pk_bf16_f32 v149, v146, v147
	v_lshl_add_u64 v[144:145], v[144:145], 0, v[130:131]
	v_mul_f32_e32 v146, 0xbfb8aa3b, v74
	v_mul_f32_e32 v147, 0xbfb8aa3b, v75
	v_exp_f32_e32 v146, v146
	v_exp_f32_e32 v147, v147
	global_store_dwordx2 v[144:145], v[148:149], off
	v_mul_f32_e32 v148, 0xbfb8aa3b, v78
	v_mul_f32_e32 v149, 0xbfb8aa3b, v79
	v_exp_f32_e32 v148, v148
	v_exp_f32_e32 v149, v149
	v_add_f32_e32 v144, 1.0, v146
	v_add_f32_e32 v145, 1.0, v147
	v_rcp_f32_e32 v144, v144
	v_rcp_f32_e32 v145, v145
	v_add_f32_e32 v148, 1.0, v148
	v_add_f32_e32 v149, 1.0, v149
	v_mul_f32_e32 v152, 0xbfb8aa3b, v66
	v_mul_f32_e32 v153, 0xbfb8aa3b, v67
	v_rcp_f32_e32 v148, v148
	v_rcp_f32_e32 v149, v149
	v_exp_f32_e32 v152, v152
	v_exp_f32_e32 v153, v153
	v_mul_f32_e32 v156, 0xbfb8aa3b, v70
	v_mul_f32_e32 v157, 0xbfb8aa3b, v71
	v_exp_f32_e32 v156, v156
	v_exp_f32_e32 v157, v157
	v_mul_f32_e32 v146, 0xbfb8aa3b, v76
	v_mul_f32_e32 v147, 0xbfb8aa3b, v77
	v_lshlrev_b32_e32 v158, 16, v142
	v_and_b32_e32 v159, 0xffff0000, v142
	v_exp_f32_e32 v146, v146
	v_exp_f32_e32 v147, v147
	v_mul_f32_e32 v150, 0xbfb8aa3b, v80
	v_mul_f32_e32 v151, 0xbfb8aa3b, v81
	v_pk_fma_f32 v[144:145], v[144:145], v[158:159], 0 op_sel_hi:[1,1,0]
	v_lshlrev_b32_e32 v158, 16, v138
	v_and_b32_e32 v159, 0xffff0000, v138
	v_exp_f32_e32 v150, v150
	v_exp_f32_e32 v151, v151
	v_add_f32_e32 v152, 1.0, v152
	v_add_f32_e32 v153, 1.0, v153
	v_mul_f32_e32 v154, 0xbfb8aa3b, v68
	v_mul_f32_e32 v155, 0xbfb8aa3b, v69
	v_pk_fma_f32 v[144:145], v[148:149], v[158:159], v[144:145]
	v_lshlrev_b32_e32 v148, 16, v136
	v_and_b32_e32 v149, 0xffff0000, v136
	v_mul_f32_e32 v136, 0xbfb8aa3b, v72
	v_rcp_f32_e32 v152, v152
	v_exp_f32_e32 v154, v154
	v_exp_f32_e32 v155, v155
	v_rcp_f32_e32 v153, v153
	v_add_f32_e32 v156, 1.0, v156
	v_add_f32_e32 v157, 1.0, v157
	v_exp_f32_e32 v136, v136
	v_mul_f32_e32 v138, 0xbfb8aa3b, v73
	v_rcp_f32_e32 v156, v156
	v_rcp_f32_e32 v157, v157
	v_exp_f32_e32 v138, v138
	v_add_f32_e32 v146, 1.0, v146
	v_add_f32_e32 v147, 1.0, v147
	v_rcp_f32_e32 v146, v146
	v_rcp_f32_e32 v147, v147
	v_add_f32_e32 v150, 1.0, v150
	v_add_f32_e32 v151, 1.0, v151
	v_rcp_f32_e32 v150, v150
	v_rcp_f32_e32 v151, v151
	v_add_f32_e32 v154, 1.0, v154
	v_add_f32_e32 v155, 1.0, v155
	v_pk_fma_f32 v[144:145], v[152:153], v[148:149], v[144:145]
	v_lshlrev_b32_e32 v148, 16, v140
	v_and_b32_e32 v149, 0xffff0000, v140
	v_add_f32_e32 v136, 1.0, v136
	v_rcp_f32_e32 v154, v154
	v_rcp_f32_e32 v155, v155
	v_pk_fma_f32 v[144:145], v[156:157], v[148:149], v[144:145]
	v_rcp_f32_e32 v148, v136
	v_add_f32_e32 v136, 1.0, v138
	v_rcp_f32_e32 v149, v136
	v_lshlrev_b32_e32 v142, 16, v143
	v_and_b32_e32 v143, 0xffff0000, v143
	v_pk_fma_f32 v[142:143], v[146:147], v[142:143], 0 op_sel_hi:[1,1,0]
	v_lshlrev_b32_e32 v138, 16, v139
	v_and_b32_e32 v139, 0xffff0000, v139
	v_pk_fma_f32 v[138:139], v[150:151], v[138:139], v[142:143]
	v_lshlrev_b32_e32 v136, 16, v137
	v_and_b32_e32 v137, 0xffff0000, v137
	v_pk_fma_f32 v[136:137], v[154:155], v[136:137], v[138:139]
	v_lshlrev_b32_e32 v138, 16, v141
	v_and_b32_e32 v139, 0xffff0000, v141
	v_lshlrev_b64 v[134:135], 12, v[134:135]
	v_pk_fma_f32 v[136:137], v[148:149], v[138:139], v[136:137]
	v_lshl_add_u64 v[134:135], s[30:31], 0, v[134:135]
	v_add_u32_e32 v162, 0x80, v184
	v_cvt_pk_bf16_f32 v138, v144, v145
	v_cvt_pk_bf16_f32 v139, v136, v137
	v_lshl_add_u64 v[134:135], v[134:135], 0, v[130:131]
	v_ashrrev_i32_e32 v163, 31, v162
	global_store_dwordx2 v[134:135], v[138:139], off
	v_lshlrev_b64 v[134:135], 14, v[162:163]
	v_lshl_add_u64 v[134:135], v[132:133], 0, v[134:135]
	v_add_co_u32_e32 v136, vcc, s99, v134
	v_add_u32_e32 v152, 0x90, v184
	s_nop 0
	v_addc_co_u32_e32 v137, vcc, 0, v135, vcc
	v_ashrrev_i32_e32 v153, 31, v152
	v_add_co_u32_e32 v138, vcc, s56, v134
	v_lshlrev_b64 v[140:141], 14, v[152:153]
	s_nop 0
	v_addc_co_u32_e32 v139, vcc, 0, v135, vcc
	v_lshl_add_u64 v[140:141], v[132:133], 0, v[140:141]
	v_add_co_u32_e32 v142, vcc, s99, v140
	v_mul_f32_e32 v148, 0xbfb8aa3b, v58
	s_nop 0
	v_addc_co_u32_e32 v143, vcc, 0, v141, vcc
	global_load_dwordx2 v[164:165], v[136:137], off offset:-4096
	global_load_dwordx2 v[166:167], v[136:137], off
	global_load_dwordx2 v[158:159], v[142:143], off offset:-4096
	global_load_dwordx2 v[154:155], v[142:143], off
	v_add_co_u32_e32 v136, vcc, s56, v140
	v_add_u32_e32 v142, 0xa0, v184
	s_nop 0
	v_addc_co_u32_e32 v137, vcc, 0, v141, vcc
	global_load_dwordx2 v[168:169], v[134:135], off
	global_load_dwordx2 v[188:189], v[138:139], off
	global_load_dwordx2 v[160:161], v[140:141], off
	global_load_dwordx2 v[156:157], v[136:137], off
	v_ashrrev_i32_e32 v143, 31, v142
	v_lshlrev_b64 v[134:135], 14, v[142:143]
	v_lshl_add_u64 v[138:139], v[132:133], 0, v[134:135]
	v_add_co_u32_e32 v136, vcc, s99, v138
	v_add_u32_e32 v134, 0xb0, v184
	s_nop 0
	v_addc_co_u32_e32 v137, vcc, 0, v139, vcc
	v_ashrrev_i32_e32 v135, 31, v134
	v_add_co_u32_e32 v140, vcc, s56, v138
	v_lshlrev_b64 v[144:145], 14, v[134:135]
	s_nop 0
	v_addc_co_u32_e32 v141, vcc, 0, v139, vcc
	v_lshl_add_u64 v[190:191], v[132:133], 0, v[144:145]
	v_add_co_u32_e32 v132, vcc, s99, v190
	v_exp_f32_e32 v185, v148
	s_nop 0
	v_addc_co_u32_e32 v133, vcc, 0, v191, vcc
	v_mul_f32_e32 v148, 0xbfb8aa3b, v59
	v_add_co_u32_e32 v192, vcc, s56, v190
	v_exp_f32_e32 v187, v148
	global_load_dwordx2 v[146:147], v[136:137], off offset:-4096
	global_load_dwordx2 v[144:145], v[136:137], off
	s_nop 0
	global_load_dwordx2 v[136:137], v[132:133], off offset:-4096
	s_nop 0
	global_load_dwordx2 v[132:133], v[132:133], off
	v_addc_co_u32_e32 v193, vcc, 0, v191, vcc
	global_load_dwordx2 v[150:151], v[138:139], off
	global_load_dwordx2 v[148:149], v[140:141], off
	s_nop 0
	global_load_dwordx2 v[140:141], v[190:191], off
	global_load_dwordx2 v[138:139], v[192:193], off
	v_add_f32_e32 v185, 1.0, v185
	v_rcp_f32_e32 v190, v185
	v_add_f32_e32 v185, 1.0, v187
	v_mul_f32_e32 v187, 0xbfb8aa3b, v60
	v_exp_f32_e32 v187, v187
	v_mul_f32_e32 v191, 0xbfb8aa3b, v61
	v_exp_f32_e32 v193, v191
	v_rcp_f32_e32 v191, v185
	v_add_f32_e32 v185, 1.0, v187
	v_mul_f32_e32 v187, 0xbfb8aa3b, v62
	v_rcp_f32_e32 v192, v185
	v_add_f32_e32 v185, 1.0, v193
	v_exp_f32_e32 v187, v187
	v_mul_f32_e32 v193, 0xbfb8aa3b, v63
	v_exp_f32_e32 v195, v193
	v_rcp_f32_e32 v193, v185
	v_add_f32_e32 v185, 1.0, v187
	v_mul_f32_e32 v187, 0xbfb8aa3b, v64
	v_rcp_f32_e32 v194, v185
	v_add_f32_e32 v185, 1.0, v195
	v_exp_f32_e32 v187, v187
	v_mul_f32_e32 v195, 0xbfb8aa3b, v65
	v_exp_f32_e32 v197, v195
	v_rcp_f32_e32 v195, v185
	v_add_f32_e32 v185, 1.0, v187
	v_mul_f32_e32 v187, 0xbfb8aa3b, v50
	v_rcp_f32_e32 v196, v185
	v_add_f32_e32 v185, 1.0, v197
	v_exp_f32_e32 v187, v187
	v_mul_f32_e32 v197, 0xbfb8aa3b, v51
	v_exp_f32_e32 v199, v197
	v_rcp_f32_e32 v197, v185
	v_add_f32_e32 v185, 1.0, v187
	v_mul_f32_e32 v187, 0xbfb8aa3b, v52
	v_rcp_f32_e32 v198, v185
	v_add_f32_e32 v185, 1.0, v199
	v_exp_f32_e32 v187, v187
	v_mul_f32_e32 v199, 0xbfb8aa3b, v53
	v_exp_f32_e32 v201, v199
	v_rcp_f32_e32 v199, v185
	v_add_f32_e32 v185, 1.0, v187
	v_mul_f32_e32 v187, 0xbfb8aa3b, v54
	v_rcp_f32_e32 v200, v185
	v_add_f32_e32 v185, 1.0, v201
	v_exp_f32_e32 v187, v187
	v_mul_f32_e32 v201, 0xbfb8aa3b, v55
	v_exp_f32_e32 v203, v201
	v_rcp_f32_e32 v201, v185
	s_waitcnt vmcnt(11)
	v_lshlrev_b32_e32 v204, 16, v168
	v_and_b32_e32 v205, 0xffff0000, v168
	v_add_f32_e32 v185, 1.0, v187
	v_pk_fma_f32 v[190:191], v[190:191], v[204:205], 0 op_sel_hi:[1,1,0]
	v_lshlrev_b32_e32 v204, 16, v164
	v_and_b32_e32 v205, 0xffff0000, v164
	v_mul_f32_e32 v164, 0xbfb8aa3b, v56
	v_rcp_f32_e32 v202, v185
	v_add_f32_e32 v185, 1.0, v203
	v_pk_fma_f32 v[190:191], v[194:195], v[204:205], v[190:191]
	v_lshlrev_b32_e32 v194, 16, v166
	v_and_b32_e32 v195, 0xffff0000, v166
	v_exp_f32_e32 v164, v164
	v_mul_f32_e32 v166, 0xbfb8aa3b, v57
	v_rcp_f32_e32 v203, v185
	v_exp_f32_e32 v166, v166
	v_pk_fma_f32 v[190:191], v[198:199], v[194:195], v[190:191]
	s_waitcnt vmcnt(10)
	v_lshlrev_b32_e32 v194, 16, v188
	v_and_b32_e32 v195, 0xffff0000, v188
	v_add_f32_e32 v164, 1.0, v164
	v_pk_fma_f32 v[190:191], v[202:203], v[194:195], v[190:191]
	v_rcp_f32_e32 v194, v164
	v_add_f32_e32 v164, 1.0, v166
	v_rcp_f32_e32 v195, v164
	v_lshlrev_b32_e32 v168, 16, v169
	v_and_b32_e32 v169, 0xffff0000, v169
	v_mul_f32_e32 v185, 0xbfb8aa3b, v34
	v_pk_fma_f32 v[168:169], v[192:193], v[168:169], 0 op_sel_hi:[1,1,0]
	v_lshlrev_b32_e32 v164, 16, v165
	v_and_b32_e32 v165, 0xffff0000, v165
	v_exp_f32_e32 v185, v185
	v_mul_f32_e32 v187, 0xbfb8aa3b, v35
	v_pk_fma_f32 v[164:165], v[196:197], v[164:165], v[168:169]
	v_lshlrev_b32_e32 v166, 16, v167
	v_and_b32_e32 v167, 0xffff0000, v167
	v_exp_f32_e32 v187, v187
	v_pk_fma_f32 v[164:165], v[200:201], v[166:167], v[164:165]
	v_lshlrev_b32_e32 v166, 16, v189
	v_and_b32_e32 v167, 0xffff0000, v189
	v_lshlrev_b64 v[162:163], 12, v[162:163]
	v_pk_fma_f32 v[164:165], v[194:195], v[166:167], v[164:165]
	v_lshl_add_u64 v[162:163], s[30:31], 0, v[162:163]
	v_cvt_pk_bf16_f32 v166, v190, v191
	v_cvt_pk_bf16_f32 v167, v164, v165
	v_lshl_add_u64 v[162:163], v[162:163], 0, v[130:131]
	v_mul_f32_e32 v164, 0xbfb8aa3b, v42
	v_mul_f32_e32 v165, 0xbfb8aa3b, v43
	v_add_f32_e32 v185, 1.0, v185
	v_exp_f32_e32 v164, v164
	v_exp_f32_e32 v165, v165
	global_store_dwordx2 v[162:163], v[166:167], off
	v_mul_f32_e32 v166, 0xbfb8aa3b, v46
	v_mul_f32_e32 v167, 0xbfb8aa3b, v47
	v_rcp_f32_e32 v188, v185
	v_add_f32_e32 v185, 1.0, v187
	v_mul_f32_e32 v187, 0xbfb8aa3b, v36
	v_exp_f32_e32 v166, v166
	v_exp_f32_e32 v167, v167
	v_exp_f32_e32 v187, v187
	v_mul_f32_e32 v189, 0xbfb8aa3b, v37
	v_exp_f32_e32 v191, v189
	v_add_f32_e32 v162, 1.0, v164
	v_add_f32_e32 v163, 1.0, v165
	v_rcp_f32_e32 v162, v162
	v_rcp_f32_e32 v163, v163
	v_add_f32_e32 v166, 1.0, v166
	v_add_f32_e32 v167, 1.0, v167
	v_rcp_f32_e32 v189, v185
	v_add_f32_e32 v185, 1.0, v187
	v_mul_f32_e32 v187, 0xbfb8aa3b, v38
	v_rcp_f32_e32 v166, v166
	v_rcp_f32_e32 v167, v167
	v_rcp_f32_e32 v190, v185
	v_add_f32_e32 v185, 1.0, v191
	v_exp_f32_e32 v187, v187
	v_mul_f32_e32 v191, 0xbfb8aa3b, v39
	v_exp_f32_e32 v193, v191
	v_mul_f32_e32 v164, 0xbfb8aa3b, v44
	v_mul_f32_e32 v165, 0xbfb8aa3b, v45
	s_waitcnt vmcnt(10)
	v_lshlrev_b32_e32 v194, 16, v160
	v_and_b32_e32 v195, 0xffff0000, v160
	v_exp_f32_e32 v164, v164
	v_exp_f32_e32 v165, v165
	v_mul_f32_e32 v168, 0xbfb8aa3b, v48
	v_mul_f32_e32 v169, 0xbfb8aa3b, v49
	v_pk_fma_f32 v[162:163], v[162:163], v[194:195], 0 op_sel_hi:[1,1,0]
	v_lshlrev_b32_e32 v194, 16, v158
	v_and_b32_e32 v195, 0xffff0000, v158
	v_exp_f32_e32 v168, v168
	v_exp_f32_e32 v169, v169
	v_rcp_f32_e32 v191, v185
	v_add_f32_e32 v185, 1.0, v187
	v_pk_fma_f32 v[162:163], v[166:167], v[194:195], v[162:163]
	v_lshlrev_b32_e32 v166, 16, v154
	v_and_b32_e32 v167, 0xffff0000, v154
	v_mul_f32_e32 v154, 0xbfb8aa3b, v40
	v_rcp_f32_e32 v192, v185
	v_add_f32_e32 v185, 1.0, v193
	v_pk_fma_f32 v[162:163], v[188:189], v[166:167], v[162:163]
	s_waitcnt vmcnt(9)
	v_lshlrev_b32_e32 v166, 16, v156
	v_and_b32_e32 v167, 0xffff0000, v156
	v_exp_f32_e32 v154, v154
	v_mul_f32_e32 v156, 0xbfb8aa3b, v41
	v_rcp_f32_e32 v193, v185
	v_exp_f32_e32 v156, v156
	v_add_f32_e32 v164, 1.0, v164
	v_add_f32_e32 v165, 1.0, v165
	v_rcp_f32_e32 v164, v164
	v_rcp_f32_e32 v165, v165
	v_add_f32_e32 v168, 1.0, v168
	v_add_f32_e32 v169, 1.0, v169
	v_rcp_f32_e32 v168, v168
	v_rcp_f32_e32 v169, v169
	v_add_f32_e32 v154, 1.0, v154
	v_pk_fma_f32 v[162:163], v[192:193], v[166:167], v[162:163]
	v_rcp_f32_e32 v166, v154
	v_add_f32_e32 v154, 1.0, v156
	v_rcp_f32_e32 v167, v154
	v_lshlrev_b32_e32 v160, 16, v161
	v_and_b32_e32 v161, 0xffff0000, v161
	v_pk_fma_f32 v[160:161], v[164:165], v[160:161], 0 op_sel_hi:[1,1,0]
	v_lshlrev_b32_e32 v158, 16, v159
	v_and_b32_e32 v159, 0xffff0000, v159
	v_pk_fma_f32 v[158:159], v[168:169], v[158:159], v[160:161]
	v_lshlrev_b32_e32 v154, 16, v155
	v_and_b32_e32 v155, 0xffff0000, v155
	v_pk_fma_f32 v[154:155], v[190:191], v[154:155], v[158:159]
	v_lshlrev_b32_e32 v156, 16, v157
	v_and_b32_e32 v157, 0xffff0000, v157
	v_lshlrev_b64 v[152:153], 12, v[152:153]
	v_pk_fma_f32 v[154:155], v[166:167], v[156:157], v[154:155]
	v_lshl_add_u64 v[152:153], s[30:31], 0, v[152:153]
	v_cvt_pk_bf16_f32 v156, v162, v163
	v_cvt_pk_bf16_f32 v157, v154, v155
	v_lshl_add_u64 v[152:153], v[152:153], 0, v[130:131]
	v_mul_f32_e32 v154, 0xbfb8aa3b, v26
	v_mul_f32_e32 v155, 0xbfb8aa3b, v27
	v_exp_f32_e32 v154, v154
	v_exp_f32_e32 v155, v155
	global_store_dwordx2 v[152:153], v[156:157], off
	v_mul_f32_e32 v156, 0xbfb8aa3b, v30
	v_mul_f32_e32 v157, 0xbfb8aa3b, v31
	v_exp_f32_e32 v156, v156
	v_exp_f32_e32 v157, v157
	v_add_f32_e32 v152, 1.0, v154
	v_add_f32_e32 v153, 1.0, v155
	v_rcp_f32_e32 v152, v152
	v_rcp_f32_e32 v153, v153
	v_add_f32_e32 v156, 1.0, v156
	v_add_f32_e32 v157, 1.0, v157
	v_mul_f32_e32 v160, 0xbfb8aa3b, v18
	v_mul_f32_e32 v161, 0xbfb8aa3b, v19
	v_rcp_f32_e32 v156, v156
	v_rcp_f32_e32 v157, v157
	v_exp_f32_e32 v160, v160
	v_exp_f32_e32 v161, v161
	v_mul_f32_e32 v164, 0xbfb8aa3b, v22
	v_mul_f32_e32 v165, 0xbfb8aa3b, v23
	v_exp_f32_e32 v164, v164
	v_exp_f32_e32 v165, v165
	v_mul_f32_e32 v154, 0xbfb8aa3b, v28
	v_mul_f32_e32 v155, 0xbfb8aa3b, v29
	s_waitcnt vmcnt(5)
	v_lshlrev_b32_e32 v166, 16, v150
	v_and_b32_e32 v167, 0xffff0000, v150
	v_exp_f32_e32 v154, v154
	v_exp_f32_e32 v155, v155
	v_mul_f32_e32 v158, 0xbfb8aa3b, v32
	v_mul_f32_e32 v159, 0xbfb8aa3b, v33
	v_pk_fma_f32 v[152:153], v[152:153], v[166:167], 0 op_sel_hi:[1,1,0]
	v_lshlrev_b32_e32 v166, 16, v146
	v_and_b32_e32 v167, 0xffff0000, v146
	v_exp_f32_e32 v158, v158
	v_exp_f32_e32 v159, v159
	v_add_f32_e32 v160, 1.0, v160
	v_add_f32_e32 v161, 1.0, v161
	v_mul_f32_e32 v162, 0xbfb8aa3b, v20
	v_mul_f32_e32 v163, 0xbfb8aa3b, v21
	v_pk_fma_f32 v[152:153], v[156:157], v[166:167], v[152:153]
	v_lshlrev_b32_e32 v156, 16, v144
	v_and_b32_e32 v157, 0xffff0000, v144
	v_mul_f32_e32 v144, 0xbfb8aa3b, v24
	v_rcp_f32_e32 v160, v160
	v_exp_f32_e32 v162, v162
	v_exp_f32_e32 v163, v163
	v_rcp_f32_e32 v161, v161
	v_add_f32_e32 v164, 1.0, v164
	v_add_f32_e32 v165, 1.0, v165
	v_exp_f32_e32 v144, v144
	v_mul_f32_e32 v146, 0xbfb8aa3b, v25
	v_rcp_f32_e32 v164, v164
	v_rcp_f32_e32 v165, v165
	v_exp_f32_e32 v146, v146
	v_add_f32_e32 v154, 1.0, v154
	v_add_f32_e32 v155, 1.0, v155
	v_rcp_f32_e32 v154, v154
	v_rcp_f32_e32 v155, v155
	v_add_f32_e32 v158, 1.0, v158
	v_add_f32_e32 v159, 1.0, v159
	v_rcp_f32_e32 v158, v158
	v_rcp_f32_e32 v159, v159
	v_add_f32_e32 v162, 1.0, v162
	v_add_f32_e32 v163, 1.0, v163
	v_pk_fma_f32 v[152:153], v[160:161], v[156:157], v[152:153]
	s_waitcnt vmcnt(4)
	v_lshlrev_b32_e32 v156, 16, v148
	v_and_b32_e32 v157, 0xffff0000, v148
	v_add_f32_e32 v144, 1.0, v144
	v_rcp_f32_e32 v162, v162
	v_rcp_f32_e32 v163, v163
	v_pk_fma_f32 v[152:153], v[164:165], v[156:157], v[152:153]
	v_rcp_f32_e32 v156, v144
	v_add_f32_e32 v144, 1.0, v146
	v_rcp_f32_e32 v157, v144
	v_lshlrev_b32_e32 v150, 16, v151
	v_and_b32_e32 v151, 0xffff0000, v151
	v_pk_fma_f32 v[150:151], v[154:155], v[150:151], 0 op_sel_hi:[1,1,0]
	v_lshlrev_b32_e32 v146, 16, v147
	v_and_b32_e32 v147, 0xffff0000, v147
	v_pk_fma_f32 v[146:147], v[158:159], v[146:147], v[150:151]
	v_lshlrev_b32_e32 v144, 16, v145
	v_and_b32_e32 v145, 0xffff0000, v145
	v_pk_fma_f32 v[144:145], v[162:163], v[144:145], v[146:147]
	v_lshlrev_b32_e32 v146, 16, v149
	v_and_b32_e32 v147, 0xffff0000, v149
	v_lshlrev_b64 v[142:143], 12, v[142:143]
	v_pk_fma_f32 v[144:145], v[156:157], v[146:147], v[144:145]
	v_lshl_add_u64 v[142:143], s[30:31], 0, v[142:143]
	v_cvt_pk_bf16_f32 v146, v152, v153
	v_cvt_pk_bf16_f32 v147, v144, v145
	v_lshl_add_u64 v[142:143], v[142:143], 0, v[130:131]
	v_mul_f32_e32 v144, 0xbfb8aa3b, v10
	v_mul_f32_e32 v145, 0xbfb8aa3b, v11
	v_exp_f32_e32 v144, v144
	v_exp_f32_e32 v145, v145
	global_store_dwordx2 v[142:143], v[146:147], off
	v_mul_f32_e32 v146, 0xbfb8aa3b, v14
	v_mul_f32_e32 v147, 0xbfb8aa3b, v15
	v_exp_f32_e32 v146, v146
	v_exp_f32_e32 v147, v147
	v_add_f32_e32 v142, 1.0, v144
	v_add_f32_e32 v143, 1.0, v145
	v_rcp_f32_e32 v142, v142
	v_rcp_f32_e32 v143, v143
	v_add_f32_e32 v146, 1.0, v146
	v_add_f32_e32 v147, 1.0, v147
	v_mul_f32_e32 v150, 0xbfb8aa3b, v6
	v_mul_f32_e32 v151, 0xbfb8aa3b, v7
	v_rcp_f32_e32 v146, v146
	v_rcp_f32_e32 v147, v147
	v_exp_f32_e32 v150, v150
	v_exp_f32_e32 v151, v151
	v_mul_f32_e32 v154, 0xbfb8aa3b, v2
	v_mul_f32_e32 v155, 0xbfb8aa3b, v3
	v_exp_f32_e32 v154, v154
	v_exp_f32_e32 v155, v155
	v_mul_f32_e32 v144, 0xbfb8aa3b, v12
	v_mul_f32_e32 v145, 0xbfb8aa3b, v13
	s_waitcnt vmcnt(4)
	v_lshlrev_b32_e32 v156, 16, v140
	v_and_b32_e32 v157, 0xffff0000, v140
	v_exp_f32_e32 v144, v144
	v_exp_f32_e32 v145, v145
	v_mul_f32_e32 v148, 0xbfb8aa3b, v16
	v_mul_f32_e32 v149, 0xbfb8aa3b, v17
	v_pk_fma_f32 v[142:143], v[142:143], v[156:157], 0 op_sel_hi:[1,1,0]
	v_lshlrev_b32_e32 v156, 16, v136
	v_and_b32_e32 v157, 0xffff0000, v136
	v_exp_f32_e32 v148, v148
	v_exp_f32_e32 v149, v149
	v_add_f32_e32 v150, 1.0, v150
	v_add_f32_e32 v151, 1.0, v151
	v_mul_f32_e32 v152, 0xbfb8aa3b, v8
	v_mul_f32_e32 v153, 0xbfb8aa3b, v9
	v_pk_fma_f32 v[142:143], v[146:147], v[156:157], v[142:143]
	v_lshlrev_b32_e32 v146, 16, v132
	v_and_b32_e32 v147, 0xffff0000, v132
	v_mul_f32_e32 v132, 0xbfb8aa3b, v4
	v_rcp_f32_e32 v150, v150
	v_exp_f32_e32 v152, v152
	v_exp_f32_e32 v153, v153
	v_rcp_f32_e32 v151, v151
	v_add_f32_e32 v154, 1.0, v154
	v_add_f32_e32 v155, 1.0, v155
	v_exp_f32_e32 v132, v132
	v_mul_f32_e32 v136, 0xbfb8aa3b, v5
	v_rcp_f32_e32 v154, v154
	v_rcp_f32_e32 v155, v155
	v_exp_f32_e32 v136, v136
	v_add_f32_e32 v144, 1.0, v144
	v_add_f32_e32 v145, 1.0, v145
	v_rcp_f32_e32 v144, v144
	v_rcp_f32_e32 v145, v145
	v_add_f32_e32 v148, 1.0, v148
	v_add_f32_e32 v149, 1.0, v149
	v_rcp_f32_e32 v148, v148
	v_rcp_f32_e32 v149, v149
	v_add_f32_e32 v152, 1.0, v152
	v_add_f32_e32 v153, 1.0, v153
	v_pk_fma_f32 v[142:143], v[150:151], v[146:147], v[142:143]
	s_waitcnt vmcnt(3)
	v_lshlrev_b32_e32 v146, 16, v138
	v_and_b32_e32 v147, 0xffff0000, v138
	v_add_f32_e32 v132, 1.0, v132
	v_rcp_f32_e32 v152, v152
	v_rcp_f32_e32 v153, v153
	v_pk_fma_f32 v[142:143], v[154:155], v[146:147], v[142:143]
	v_rcp_f32_e32 v146, v132
	v_add_f32_e32 v132, 1.0, v136
	v_rcp_f32_e32 v147, v132
	v_lshlrev_b32_e32 v140, 16, v141
	v_and_b32_e32 v141, 0xffff0000, v141
	v_pk_fma_f32 v[140:141], v[144:145], v[140:141], 0 op_sel_hi:[1,1,0]
	v_lshlrev_b32_e32 v136, 16, v137
	v_and_b32_e32 v137, 0xffff0000, v137
	v_pk_fma_f32 v[136:137], v[148:149], v[136:137], v[140:141]
	v_lshlrev_b32_e32 v132, 16, v133
	v_and_b32_e32 v133, 0xffff0000, v133
	v_pk_fma_f32 v[132:133], v[152:153], v[132:133], v[136:137]
	v_lshlrev_b32_e32 v136, 16, v139
	v_and_b32_e32 v137, 0xffff0000, v139
	v_pk_fma_f32 v[132:133], v[146:147], v[136:137], v[132:133]
	v_cvt_pk_bf16_f32 v136, v142, v143
	v_cvt_pk_bf16_f32 v137, v132, v133
	v_lshlrev_b64 v[132:133], 12, v[134:135]
	v_lshl_add_u64 v[132:133], s[30:31], 0, v[132:133]
	v_lshl_add_u64 v[130:131], v[132:133], 0, v[130:131]
	global_store_dwordx2 v[130:131], v[136:137], off
